# post-finish barrier replaced by per-token-tile completion counters; post-GU barriers kept global (bounded XCD drift); last layer's post-GU2 barrier XCD-local
# baseline (speedup 1.0000x reference)
; __device__ __forceinline__ unsigned xb_ld(unsigned* p)              { return __hip_atomic_load(p, __ATOMIC_RELAXED, __HIP_MEMORY_SCOPE_AGENT); }
; __device__ __forceinline__ unsigned xb_add(unsigned* p, unsigned v) { return __hip_atomic_fetch_add(p, v, __ATOMIC_RELAXED, __HIP_MEMORY_SCOPE_AGENT); }
; #define XB_SPIN(cond, bar) do { unsigned _sp = 0; while (cond) { __builtin_amdgcn_s_sleep(1); \
;     if ((++_sp & 255u) == 0u) { if (xb_ld(&(bar)[XB_TMO])) break; if (_sp > XB_SPIN_CAP) { atomicAdd(&(bar)[XB_TMO], 1u); break; } } } } while (0)
; __device__ __forceinline__ void xcd_barrier(const XcdBarrier& b) {
;     ...
;             __builtin_amdgcn_fence(__ATOMIC_RELEASE, "agent");
;             asm volatile("s_waitcnt vmcnt(0)" ::: "memory");
;             const unsigned og = xb_add(&bar[XB_TOP], 1u);
;             const unsigned tg = og / nx;
;             if (og + 1u == (tg + 1u) * nx) xb_add(&bar[XB_TOPGEN], 1u);
;             else XB_SPIN(xb_ld(&bar[XB_TOPGEN]) == tg, bar);
.LBB0_637:
	s_andn2_saveexec_b64 s[28:29], s[28:29]
	s_cbranch_execz .LBB0_657
	s_mov_b64 s[28:29], exec
	v_mov_b32_e32 v5, 0x2000c
	ds_read_b32 v5, v5
	s_waitcnt lgkmcnt(0)
	v_readfirstlane_b32 s4, v5
	s_cmp_lg_u32 s4, 0
	s_cbranch_scc1 .Lsyncg_global
	v_readlane_b32 s4, v254, 51
	v_readlane_b32 s5, v255, 10
	s_and_b32 s5, s5, 4
	s_add_i32 s4, s4, s5
	s_cmp_eq_u32 s4, 7
	s_cbranch_scc1 .Lsyncg_local
